# scan step 4 o-part: fragment LDS reads batched with counted waits (V^T fragments reloaded for the S update)
# speedup vs baseline: 1.0167x; 1.0062x over previous
.LBB0_330:
	s_andn2_saveexec_b64 s[0:1], s[0:1]
	s_or_b64 exec, exec, s[0:1]
	v_cvt_pk_bf16_f32 v90, v90, v91
	v_cvt_pk_bf16_f32 v91, v92, v93
	v_add_u32_e32 v92, v210, v154
	v_add_u32_e32 v94, v202, v200
	ds_write_b64 v92, v[90:91] offset:40960
	s_waitcnt lgkmcnt(0)
	s_barrier
	ds_read_b128 v[102:105], v94 offset:24576
	v_add_u32_e32 v95, v202, v201
	ds_read_b128 v[90:93], v95 offset:24576
	ds_read_b128 v[98:101], v94 offset:26624
	ds_read_b128 v[94:97], v95 offset:26624
	ds_read_b128 v[210:213], v209 offset:40960
	ds_read_b128 v[242:245], v2 offset:40960
	ds_read_b128 v[218:221], v209 offset:43008
	ds_read_b128 v[246:249], v2 offset:43008
	ds_read_b128 v[226:229], v209 offset:45056
	ds_read_b128 v[250:253], v2 offset:45056
	ds_read_b128 v[234:237], v209 offset:47104
	v_ashrrev_i32_e32 v135, 31, v134
	s_mov_b64 s[0:1], -1
	s_and_b64 vcc, exec, s[4:5]
	s_waitcnt lgkmcnt(6)
	v_mfma_f32_16x16x32_bf16 v[214:217], v[102:105], v[210:213], 0
	v_mfma_f32_16x16x32_bf16 v[210:213], v[98:101], v[210:213], 0
	s_waitcnt lgkmcnt(5)
	v_mfma_f32_16x16x32_bf16 v[214:217], v[90:93], v[242:245], v[214:217]
	v_mfma_f32_16x16x32_bf16 v[210:213], v[94:97], v[242:245], v[210:213]
	ds_read_b128 v[242:245], v2 offset:47104
	s_waitcnt lgkmcnt(5)
	v_mfma_f32_16x16x32_bf16 v[222:225], v[102:105], v[218:221], 0
	v_mfma_f32_16x16x32_bf16 v[218:221], v[98:101], v[218:221], 0
	s_waitcnt lgkmcnt(4)
	v_mfma_f32_16x16x32_bf16 v[222:225], v[90:93], v[246:249], v[222:225]
	v_mfma_f32_16x16x32_bf16 v[218:221], v[94:97], v[246:249], v[218:221]
	s_waitcnt lgkmcnt(3)
	v_mfma_f32_16x16x32_bf16 v[230:233], v[102:105], v[226:229], 0
	v_mfma_f32_16x16x32_bf16 v[226:229], v[98:101], v[226:229], 0
	s_waitcnt lgkmcnt(2)
	v_mfma_f32_16x16x32_bf16 v[230:233], v[90:93], v[250:253], v[230:233]
	v_mfma_f32_16x16x32_bf16 v[226:229], v[94:97], v[250:253], v[226:229]
	s_waitcnt lgkmcnt(1)
	v_mfma_f32_16x16x32_bf16 v[238:241], v[102:105], v[234:237], 0
	v_mfma_f32_16x16x32_bf16 v[234:237], v[98:101], v[234:237], 0
	s_waitcnt lgkmcnt(0)
	v_mfma_f32_16x16x32_bf16 v[238:241], v[90:93], v[242:245], v[238:241]
	v_mfma_f32_16x16x32_bf16 v[234:237], v[94:97], v[242:245], v[234:237]
	ds_read_b128 v[246:249], v206 offset:49152
	ds_read_b128 v[250:253], v206 offset:51200
	ds_read_b128 v[90:93], v209
	ds_read_b128 v[94:97], v209 offset:2048
	ds_read_b128 v[98:101], v209 offset:4096
	ds_read_b128 v[102:105], v209 offset:6144
	ds_read_b128 v[242:245], v207 offset:49152
	s_waitcnt lgkmcnt(4)
	v_mfma_f32_16x16x32_bf16 v[214:217], v[246:249], v[90:93], v[214:217]
	s_waitcnt lgkmcnt(3)
	v_mfma_f32_16x16x32_bf16 v[222:225], v[246:249], v[94:97], v[222:225]
	s_waitcnt lgkmcnt(2)
	v_mfma_f32_16x16x32_bf16 v[230:233], v[246:249], v[98:101], v[230:233]
	s_waitcnt lgkmcnt(1)
	v_mfma_f32_16x16x32_bf16 v[238:241], v[246:249], v[102:105], v[238:241]
	ds_read_b128 v[246:249], v207 offset:51200
	v_mfma_f32_16x16x32_bf16 v[210:213], v[250:253], v[90:93], v[210:213]
	ds_read_b128 v[90:93], v2
	v_mfma_f32_16x16x32_bf16 v[218:221], v[250:253], v[94:97], v[218:221]
	ds_read_b128 v[94:97], v2 offset:2048
	v_mfma_f32_16x16x32_bf16 v[226:229], v[250:253], v[98:101], v[226:229]
	ds_read_b128 v[98:101], v2 offset:4096
	v_mfma_f32_16x16x32_bf16 v[234:237], v[250:253], v[102:105], v[234:237]
	ds_read_b128 v[102:105], v2 offset:6144
	s_waitcnt lgkmcnt(3)
	v_mfma_f32_16x16x32_bf16 v[214:217], v[242:245], v[90:93], v[214:217]
	v_mfma_f32_16x16x32_bf16 v[210:213], v[246:249], v[90:93], v[210:213]
	s_waitcnt lgkmcnt(2)
	v_mfma_f32_16x16x32_bf16 v[222:225], v[242:245], v[94:97], v[222:225]
	v_mfma_f32_16x16x32_bf16 v[218:221], v[246:249], v[94:97], v[218:221]
	s_waitcnt lgkmcnt(1)
	v_mfma_f32_16x16x32_bf16 v[230:233], v[242:245], v[98:101], v[230:233]
	v_mfma_f32_16x16x32_bf16 v[226:229], v[246:249], v[98:101], v[226:229]
	s_waitcnt lgkmcnt(0)
	v_mfma_f32_16x16x32_bf16 v[238:241], v[242:245], v[102:105], v[238:241]
	v_mfma_f32_16x16x32_bf16 v[234:237], v[246:249], v[102:105], v[234:237]
	v_add_u32_e32 v242, v202, v200
	v_add_u32_e32 v243, v202, v201
	ds_read_b128 v[102:105], v242 offset:24576
	ds_read_b128 v[90:93], v243 offset:24576
	ds_read_b128 v[98:101], v242 offset:26624
	ds_read_b128 v[94:97], v243 offset:26624
	v_mbcnt_lo_u32_b32 v242, -1, 0
	v_mbcnt_hi_u32_b32 v242, -1, v242
	v_bfe_u32 v242, v242, 4, 1
	v_mul_u32_u24_e32 v242, 24, v242
	v_mov_b32_e32 v243, 0
	v_cvt_pk_bf16_f32 v244, v214, v215
	v_cvt_pk_bf16_f32 v245, v216, v217
	v_cvt_pk_bf16_f32 v246, v210, v211
	v_cvt_pk_bf16_f32 v247, v212, v213
	v_cvt_pk_bf16_f32 v248, v222, v223
	v_cvt_pk_bf16_f32 v249, v224, v225
	v_cvt_pk_bf16_f32 v250, v218, v219
	v_cvt_pk_bf16_f32 v251, v220, v221
	v_cvt_pk_bf16_f32 v212, v230, v231
	v_cvt_pk_bf16_f32 v213, v232, v233
	v_cvt_pk_bf16_f32 v214, v226, v227
	v_cvt_pk_bf16_f32 v215, v228, v229
	v_lshl_add_u64 v[252:253], v[132:133], 0, v[242:243]
	v_subrev_u32_e32 v220, 48, v134
	v_ashrrev_i32_e32 v221, 31, v220
	v_lshlrev_b64 v[220:221], 11, v[220:221]
	v_lshl_add_u64 v[220:221], v[252:253], 0, v[220:221]
	v_subrev_u32_e32 v222, 32, v134
	v_ashrrev_i32_e32 v223, 31, v222
	v_lshlrev_b64 v[222:223], 11, v[222:223]
	v_lshl_add_u64 v[222:223], v[252:253], 0, v[222:223]
	v_add_u32_e32 v224, -16, v134
	v_ashrrev_i32_e32 v225, 31, v224
	v_lshlrev_b64 v[224:225], 11, v[224:225]
	v_lshl_add_u64 v[224:225], v[252:253], 0, v[224:225]
	v_lshlrev_b64 v[226:227], 11, v[134:135]
	v_lshl_add_u64 v[226:227], v[252:253], 0, v[226:227]
	v_cvt_pk_bf16_f32 v216, v238, v239
	v_cvt_pk_bf16_f32 v217, v240, v241
	v_cvt_pk_bf16_f32 v218, v234, v235
	v_cvt_pk_bf16_f32 v219, v236, v237
	v_permlane16_swap_b32_e32 v244, v246
	v_permlane16_swap_b32_e32 v245, v247
	global_store_dwordx4 v[220:221], v[244:247], off
	v_permlane16_swap_b32_e32 v248, v250
	v_permlane16_swap_b32_e32 v249, v251
	global_store_dwordx4 v[222:223], v[248:251], off
	v_permlane16_swap_b32_e32 v212, v214
	v_permlane16_swap_b32_e32 v213, v215
	global_store_dwordx4 v[224:225], v[212:215], off
	v_permlane16_swap_b32_e32 v216, v218
	v_permlane16_swap_b32_e32 v217, v219
	global_store_dwordx4 v[226:227], v[216:219], off
	s_nop 3
	ds_read_b128 v[218:221], v208
	ds_read_b128 v[222:225], v208 offset:64
	ds_read_b128 v[226:229], v208 offset:128
	ds_read_b128 v[230:233], v208 offset:192
	ds_read_b128 v[234:237], v209 offset:16384
	ds_read_b128 v[238:241], v209 offset:18432
	ds_read_b128 v[242:245], v209 offset:20480
	ds_read_b128 v[246:249], v209 offset:22528
	ds_read_b128 v[250:253], v2 offset:16384
	s_waitcnt lgkmcnt(8)
	v_pk_mul_f32 v[22:23], v[22:23], v[218:219]
	v_pk_mul_f32 v[24:25], v[24:25], v[220:221]
	v_pk_mul_f32 v[26:27], v[26:27], v[218:219]
	v_pk_mul_f32 v[28:29], v[28:29], v[220:221]
	s_waitcnt lgkmcnt(7)
	v_pk_mul_f32 v[30:31], v[30:31], v[222:223]
	v_pk_mul_f32 v[32:33], v[32:33], v[224:225]
	v_pk_mul_f32 v[34:35], v[34:35], v[222:223]
	v_pk_mul_f32 v[36:37], v[36:37], v[224:225]
	s_waitcnt lgkmcnt(6)
	v_pk_mul_f32 v[38:39], v[38:39], v[226:227]
	v_pk_mul_f32 v[40:41], v[40:41], v[228:229]
	v_pk_mul_f32 v[42:43], v[42:43], v[226:227]
	v_pk_mul_f32 v[44:45], v[44:45], v[228:229]
	s_waitcnt lgkmcnt(5)
	v_pk_mul_f32 v[46:47], v[46:47], v[230:231]
	v_pk_mul_f32 v[48:49], v[48:49], v[232:233]
	v_pk_mul_f32 v[50:51], v[50:51], v[230:231]
	v_pk_mul_f32 v[52:53], v[52:53], v[232:233]
	ds_read_b128 v[218:221], v2 offset:18432
	ds_read_b128 v[222:225], v2 offset:20480
	ds_read_b128 v[226:229], v2 offset:22528
	s_waitcnt lgkmcnt(7)
	v_mfma_f32_16x16x32_bf16 v[22:25], v[234:237], v[102:105], v[22:25]
	v_mfma_f32_16x16x32_bf16 v[26:29], v[234:237], v[98:101], v[26:29]
	s_waitcnt lgkmcnt(6)
	v_mfma_f32_16x16x32_bf16 v[30:33], v[238:241], v[102:105], v[30:33]
	v_mfma_f32_16x16x32_bf16 v[34:37], v[238:241], v[98:101], v[34:37]
	s_waitcnt lgkmcnt(5)
	v_mfma_f32_16x16x32_bf16 v[38:41], v[242:245], v[102:105], v[38:41]
	v_mfma_f32_16x16x32_bf16 v[42:45], v[242:245], v[98:101], v[42:45]
	s_waitcnt lgkmcnt(4)
	v_mfma_f32_16x16x32_bf16 v[46:49], v[246:249], v[102:105], v[46:49]
	v_mfma_f32_16x16x32_bf16 v[50:53], v[246:249], v[98:101], v[50:53]
	s_waitcnt lgkmcnt(3)
	v_mfma_f32_16x16x32_bf16 v[22:25], v[250:253], v[90:93], v[22:25]
	v_mfma_f32_16x16x32_bf16 v[26:29], v[250:253], v[94:97], v[26:29]
	s_waitcnt lgkmcnt(2)
	v_mfma_f32_16x16x32_bf16 v[30:33], v[218:221], v[90:93], v[30:33]
	v_mfma_f32_16x16x32_bf16 v[34:37], v[218:221], v[94:97], v[34:37]
	s_waitcnt lgkmcnt(1)
	v_mfma_f32_16x16x32_bf16 v[38:41], v[222:225], v[90:93], v[38:41]
	v_mfma_f32_16x16x32_bf16 v[42:45], v[222:225], v[94:97], v[42:45]
	s_waitcnt lgkmcnt(0)
	v_mfma_f32_16x16x32_bf16 v[46:49], v[226:229], v[90:93], v[46:49]
	v_mfma_f32_16x16x32_bf16 v[50:53], v[226:229], v[94:97], v[50:53]
	s_nop 1
	v_cvt_pk_bf16_f32 v90, v22, v23
	v_cvt_pk_bf16_f32 v91, v24, v25
	v_cvt_pk_bf16_f32 v92, v26, v27
	v_cvt_pk_bf16_f32 v93, v28, v29
	ds_write2st64_b64 v146, v[90:91], v[92:93] offset0:96 offset1:100
	v_cvt_pk_bf16_f32 v90, v30, v31
	v_cvt_pk_bf16_f32 v91, v32, v33
	v_cvt_pk_bf16_f32 v92, v34, v35
	v_cvt_pk_bf16_f32 v93, v36, v37
	ds_write2st64_b64 v149, v[90:91], v[92:93] offset0:96 offset1:100
	v_cvt_pk_bf16_f32 v90, v38, v39
	v_cvt_pk_bf16_f32 v91, v40, v41
	v_cvt_pk_bf16_f32 v92, v42, v43
	v_cvt_pk_bf16_f32 v93, v44, v45
	ds_write2st64_b64 v152, v[90:91], v[92:93] offset0:96 offset1:100
	v_cvt_pk_bf16_f32 v90, v46, v47
	v_cvt_pk_bf16_f32 v91, v48, v49
	v_cvt_pk_bf16_f32 v92, v50, v51
	v_cvt_pk_bf16_f32 v93, v52, v53
	ds_write2st64_b64 v155, v[90:91], v[92:93] offset0:96 offset1:100
	s_waitcnt lgkmcnt(0)
	s_barrier
	s_cbranch_vccnz .LBB0_332
	s_mov_b64 s[0:1], 0
	s_waitcnt vmcnt(12)
	ds_write_b128 v156, v[86:89]
	s_waitcnt vmcnt(11)
	ds_write_b128 v156, v[82:85] offset:8192
	s_waitcnt vmcnt(10)
	ds_write_b128 v156, v[78:81] offset:4096
	s_waitcnt vmcnt(9)
	ds_write_b128 v156, v[74:77] offset:12288
